# attention work queues: when a queue is found exhausted the remaining seven heads are checked in one parallel sweep instead of one barrier-fenced round trip each
# speedup vs baseline: 1.0081x; 1.0081x over previous
.LBB0_1098:
	s_add_i32 s31, s31, 1
	s_cmp_lg_u32 s31, 8
	s_cbranch_scc0 .LBB0_1126
	s_barrier
	v_cmp_gt_u32_e32 vcc, 8, v226
	s_and_saveexec_b64 s[4:5], vcc
	s_cbranch_execz .Lq_sweep_done
	s_load_dwordx2 s[6:7], s[0:1], 0x58
	v_readlane_b32 s8, v254, 0
	s_lshl_b32 s9, s30, 2
	v_add_u32_e32 v0, s8, v226
	v_and_b32_e32 v0, 7, v0
	v_lshlrev_b32_e32 v0, 6, v0
	v_add_u32_e32 v0, s9, v0
	v_add_u32_e32 v0, 0x1a980000, v0
	s_waitcnt lgkmcnt(0)
	global_load_dword v1, v0, s[6:7] sc1
	s_waitcnt vmcnt(0)
	v_cmp_gt_u32_e32 vcc, 64, v1
	s_nop 1
	s_lshr_b32 s8, vcc_lo, s31
	s_ff1_i32_b32 s9, s8
	s_add_i32 s9, s9, s31
	s_cmp_eq_u32 s8, 0
	s_cselect_b32 s9, 8, s9
	v_mov_b32_e32 v0, s9
	v_mov_b32_e32 v1, s48
	ds_write_b32 v1, v0
.Lq_sweep_done:
	s_or_b64 exec, exec, s[4:5]
	v_mov_b32_e32 v0, s48
	s_waitcnt lgkmcnt(0)
	s_barrier
	ds_read_b32 v0, v0
	s_waitcnt lgkmcnt(0)
	v_readfirstlane_b32 s31, v0
	s_nop 0
	s_cmp_lg_u32 s31, 8
	s_cbranch_scc0 .LBB0_1126
